# early L1 invalidate + flat barrier: every leader polls the cross-XCD arrival counter (no generation words, no per-XCD relay)
# baseline (speedup 1.0000x reference)
; DI unsigned xb_ld(unsigned* q) { return __hip_atomic_load(q, __ATOMIC_RELAXED, __HIP_MEMORY_SCOPE_AGENT); }
; DI unsigned xb_add(unsigned* q, unsigned v) { return __hip_atomic_fetch_add(q, v, __ATOMIC_RELAXED, __HIP_MEMORY_SCOPE_AGENT); }
; #define XB_SPIN(cond, bar) do { unsigned _sp = 0; while (cond) { __builtin_amdgcn_s_sleep(1); \
;     if ((++_sp & 255u) == 0u) { if (xb_ld(&(bar)[XB_TMO])) break; if (_sp > XB_SPIN_CAP) { atomicAdd(&(bar)[XB_TMO], 1u); break; } } } } while (0)
; DI void grid_bar(unsigned* bar, volatile LAS unsigned* st, int wid) {
;     ...
;             const unsigned old = xb_add(&bar[XB_XSUB(x)], 1u);
;             const unsigned gen = old / nloc;
;             if (old + 1u == (gen + 1u) * nloc) {
;                 __builtin_amdgcn_fence(__ATOMIC_RELEASE, "agent");
;                 asm volatile("s_waitcnt vmcnt(0)" ::: "memory");
;                 const unsigned og = xb_add(&bar[XB_TOP], 1u);
;                 const unsigned tg = og / nx;
;                 if (og + 1u == (tg + 1u) * nx) xb_add(&bar[XB_TOPGEN], 1u);
;                 else XB_SPIN(xb_ld(&bar[XB_TOPGEN]) == tg, bar);
;                 __builtin_amdgcn_fence(__ATOMIC_ACQUIRE, "agent");
;                 xb_add(&bar[XB_XGEN(x)], 1u);
;                 asm volatile("s_waitcnt vmcnt(0)" ::: "memory");
;             } else {
;                 XB_SPIN(xb_ld(&bar[XB_XGEN(x)]) == gen, bar);
.LBB0_261:
	s_or_b64 exec, exec, s[14:15]
	v_cvt_f32_u32_e32 v4, v2
	s_waitcnt vmcnt(0)
	v_readfirstlane_b32 s12, v3
	buffer_inv sc1
	v_sub_u32_e32 v3, 0, v2
	v_rcp_iflag_f32_e32 v4, v4
	v_add_u32_e32 v5, s12, v1
	v_mul_f32_e32 v4, 0x4f7ffffe, v4
	v_cvt_u32_f32_e32 v4, v4
	v_mul_lo_u32 v1, v3, v4
	v_mul_hi_u32 v1, v4, v1
	v_add_u32_e32 v1, v4, v1
	v_mul_hi_u32 v1, v5, v1
	v_mul_lo_u32 v3, v1, v2
	v_sub_u32_e32 v3, v5, v3
	v_add_u32_e32 v4, 1, v1
	v_cmp_ge_u32_e32 vcc, v3, v2
	s_nop 1
	v_cndmask_b32_e32 v1, v1, v4, vcc
	v_sub_u32_e32 v4, v3, v2
	v_cndmask_b32_e32 v3, v3, v4, vcc
	v_add_u32_e32 v4, 1, v1
	v_cmp_ge_u32_e32 vcc, v3, v2
	v_add_u32_e32 v3, 1, v5
	s_nop 0
	v_cndmask_b32_e32 v1, v1, v4, vcc
	v_mul_lo_u32 v4, v2, v1
	v_add_u32_e32 v2, v4, v2
	v_cmp_ne_u32_e32 vcc, v3, v2
	s_and_saveexec_b64 s[12:13], vcc
	s_xor_b64 s[12:13], exec, s[12:13]
	s_cbranch_execz .LBB0_275
	s_waitcnt lgkmcnt(0)
	v_add_u32_e32 v4, 1, v1
	v_mul_lo_u32 v4, v4, v0
	v_mov_b32_e32 v2, 0xcd83000
	s_mov_b32 s28, 0

; DI unsigned xb_ld(unsigned* q) { return __hip_atomic_load(q, __ATOMIC_RELAXED, __HIP_MEMORY_SCOPE_AGENT); }
; DI unsigned xb_add(unsigned* q, unsigned v) { return __hip_atomic_fetch_add(q, v, __ATOMIC_RELAXED, __HIP_MEMORY_SCOPE_AGENT); }
; #define XB_SPIN(cond, bar) do { unsigned _sp = 0; while (cond) { __builtin_amdgcn_s_sleep(1); \
;     if ((++_sp & 255u) == 0u) { if (xb_ld(&(bar)[XB_TMO])) break; if (_sp > XB_SPIN_CAP) { atomicAdd(&(bar)[XB_TMO], 1u); break; } } } } while (0)
; DI void grid_bar(unsigned* bar, volatile LAS unsigned* st, int wid) {
;     ...
;             if (old + 1u == (gen + 1u) * nloc) {
;                 __builtin_amdgcn_fence(__ATOMIC_RELEASE, "agent");
;                 asm volatile("s_waitcnt vmcnt(0)" ::: "memory");
;                 const unsigned og = xb_add(&bar[XB_TOP], 1u);
;                 const unsigned tg = og / nx;
;                 if (og + 1u == (tg + 1u) * nx) xb_add(&bar[XB_TOPGEN], 1u);
;                 else XB_SPIN(xb_ld(&bar[XB_TOPGEN]) == tg, bar);
;                 __builtin_amdgcn_fence(__ATOMIC_ACQUIRE, "agent");
;                 xb_add(&bar[XB_XGEN(x)], 1u);
;                 asm volatile("s_waitcnt vmcnt(0)" ::: "memory");
;             } else {
;                 XB_SPIN(xb_ld(&bar[XB_XGEN(x)]) == gen, bar);
;                 __builtin_amdgcn_fence(__ATOMIC_ACQUIRE, "agent");
;                 asm volatile("s_waitcnt vmcnt(0)" ::: "memory");
.Lxb2_0_done:
	s_mov_b64 s[8:9], exec
	v_mbcnt_lo_u32_b32 v0, s8, 0
	v_mbcnt_hi_u32_b32 v0, s9, v0
	v_cmp_eq_u32_e32 vcc, 0, v0
	s_waitcnt vmcnt(0)
	s_and_saveexec_b64 s[12:13], vcc
	s_cbranch_execz .LBB0_294
	s_bcnt1_i32_b64 s8, s[8:9]
	v_mov_b32_e32 v0, 0x2000
	v_mov_b32_e32 v1, s8
	s_nop 0
